# P6 and P15 GEMM k-loops: LDS fragment reads rescheduled two k-steps ahead (same MFMAs, same order)
# speedup vs baseline: 1.0382x; 1.0105x over previous
.LBB0_1721:
	s_or_b64 exec, exec, s[20:21]
	v_add_u32_e32 v4, s35, v158
	v_ashrrev_i32_e32 v5, 31, v4
	v_lshlrev_b64 v[4:5], 11, v[4:5]
	v_lshl_add_u64 v[140:141], s[82:83], 0, v[4:5]
	v_add_u32_e32 v4, s35, v159
	v_ashrrev_i32_e32 v5, 31, v4
	v_lshlrev_b64 v[4:5], 11, v[4:5]
	v_lshl_add_u64 v[144:145], s[82:83], 0, v[4:5]
	v_add_u32_e32 v4, s35, v160
	v_ashrrev_i32_e32 v5, 31, v4
	v_lshlrev_b64 v[4:5], 11, v[4:5]
	v_lshl_add_u64 v[148:149], s[82:83], 0, v[4:5]
	v_add_u32_e32 v4, s35, v1
	v_ashrrev_i32_e32 v5, 31, v4
	v_lshlrev_b64 v[4:5], 11, v[4:5]
	v_lshl_add_u64 v[138:139], s[82:83], 0, v[48:49]
	v_lshl_add_u64 v[142:143], s[82:83], 0, v[42:43]
	v_lshl_add_u64 v[146:147], s[82:83], 0, v[36:37]
	v_lshl_add_u64 v[150:151], s[82:83], 0, v[34:35]
	v_lshl_add_u64 v[152:153], s[82:83], 0, v[4:5]
	s_mov_b32 s37, 0
	v_mov_b32_e32 v3, v2
	v_mov_b32_e32 v4, v2
	v_mov_b32_e32 v5, v2
	v_mov_b32_e32 v6, v2
	v_mov_b32_e32 v7, v2
	v_mov_b32_e32 v8, v2
	v_mov_b32_e32 v9, v2
	v_mov_b32_e32 v10, v2
	v_mov_b32_e32 v11, v2
	v_mov_b32_e32 v12, v2
	v_mov_b32_e32 v13, v2
	v_mov_b32_e32 v14, v2
	v_mov_b32_e32 v15, v2
	v_mov_b32_e32 v16, v2
	v_mov_b32_e32 v17, v2
	v_mov_b32_e32 v18, v2
	v_mov_b32_e32 v19, v2
	v_mov_b32_e32 v20, v2
	v_mov_b32_e32 v21, v2
	v_mov_b32_e32 v22, v2
	v_mov_b32_e32 v23, v2
	v_mov_b32_e32 v24, v2
	v_mov_b32_e32 v25, v2
	v_mov_b32_e32 v26, v2
	v_mov_b32_e32 v27, v2
	v_mov_b32_e32 v28, v2
	v_mov_b32_e32 v29, v2
	v_mov_b32_e32 v30, v2
	v_mov_b32_e32 v31, v2
	v_mov_b32_e32 v32, v2
	v_mov_b32_e32 v33, v2
	v_mov_b32_e32 v34, v2
	v_mov_b32_e32 v35, v2
	v_mov_b32_e32 v36, v2
	v_mov_b32_e32 v37, v2
	v_mov_b32_e32 v38, v2
	v_mov_b32_e32 v39, v2
	v_mov_b32_e32 v40, v2
	v_mov_b32_e32 v41, v2
	v_mov_b32_e32 v42, v2
	v_mov_b32_e32 v43, v2
	v_mov_b32_e32 v44, v2
	v_mov_b32_e32 v45, v2
	v_mov_b32_e32 v46, v2
	v_mov_b32_e32 v47, v2
	v_mov_b32_e32 v48, v2
	v_mov_b32_e32 v49, v2
	v_mov_b32_e32 v50, v2
	v_mov_b32_e32 v51, v2
	v_mov_b32_e32 v52, v2
	v_mov_b32_e32 v53, v2
	v_mov_b32_e32 v54, v2
	v_mov_b32_e32 v55, v2
	v_mov_b32_e32 v56, v2
	v_mov_b32_e32 v57, v2
	v_mov_b32_e32 v58, v2
	v_mov_b32_e32 v59, v2
	v_mov_b32_e32 v60, v2
	v_mov_b32_e32 v61, v2
	v_mov_b32_e32 v62, v2
	v_mov_b32_e32 v63, v2
	v_mov_b32_e32 v64, v2
	v_mov_b32_e32 v65, v2
	s_waitcnt lgkmcnt(0)
	s_barrier
	ds_read_b128 v[192:195], v161 offset:0
	ds_read_b128 v[196:199], v162 offset:18432
	ds_read_b128 v[200:203], v162 offset:23040
	ds_read_b128 v[204:207], v161 offset:4608
	ds_read_b128 v[208:211], v161 offset:32
	ds_read_b128 v[212:215], v162 offset:18464
	ds_read_b128 v[216:219], v162 offset:23072
	ds_read_b128 v[220:223], v161 offset:4640
	s_branch .LBB0_1724

.LBB0_1723:
	s_add_i32 s37, s37, 2
	v_lshl_add_u64 v[138:139], v[138:139], 0, s[18:19]
	v_lshl_add_u64 v[140:141], v[140:141], 0, s[18:19]
	v_lshl_add_u64 v[142:143], v[142:143], 0, s[18:19]
	v_lshl_add_u64 v[144:145], v[144:145], 0, s[18:19]
	v_lshl_add_u64 v[146:147], v[146:147], 0, s[18:19]
	v_lshl_add_u64 v[148:149], v[148:149], 0, s[18:19]
	v_lshl_add_u64 v[150:151], v[150:151], 0, s[18:19]
	v_lshl_add_u64 v[152:153], v[152:153], 0, s[18:19]
	s_andn2_b64 vcc, exec, s[20:21]
	s_waitcnt lgkmcnt(4)
	v_mfma_f32_32x32x16_bf16 v[50:65], v[192:195], v[196:199], v[50:65]
	v_mfma_f32_32x32x16_bf16 v[34:49], v[192:195], v[200:203], v[34:49]
	v_mfma_f32_32x32x16_bf16 v[18:33], v[204:207], v[196:199], v[18:33]
	v_mfma_f32_32x32x16_bf16 v[2:17], v[204:207], v[200:203], v[2:17]
	ds_read_b128 v[164:167], v161 offset:36928
	ds_read_b128 v[168:171], v162 offset:55360
	ds_read_b128 v[172:175], v162 offset:59968
	ds_read_b128 v[176:179], v161 offset:41536
	s_waitcnt lgkmcnt(4)
	v_mfma_f32_32x32x16_bf16 v[50:65], v[208:211], v[212:215], v[50:65]
	v_mfma_f32_32x32x16_bf16 v[34:49], v[208:211], v[216:219], v[34:49]
	v_mfma_f32_32x32x16_bf16 v[18:33], v[220:223], v[212:215], v[18:33]
	v_mfma_f32_32x32x16_bf16 v[2:17], v[220:223], v[216:219], v[2:17]
	ds_read_b128 v[180:183], v161 offset:36960
	ds_read_b128 v[184:187], v162 offset:55392
	ds_read_b128 v[188:191], v162 offset:60000
	ds_read_b128 v[224:227], v161 offset:41568
	s_waitcnt lgkmcnt(4)
	v_mfma_f32_32x32x16_bf16 v[50:65], v[164:167], v[168:171], v[50:65]
	v_mfma_f32_32x32x16_bf16 v[34:49], v[164:167], v[172:175], v[34:49]
	s_waitcnt lgkmcnt(0)
	s_barrier
	ds_read_b128 v[192:195], v161 offset:0
	ds_read_b128 v[196:199], v162 offset:18432
	ds_read_b128 v[200:203], v162 offset:23040
	ds_read_b128 v[204:207], v161 offset:4608
	ds_read_b128 v[208:211], v161 offset:32
	ds_read_b128 v[212:215], v162 offset:18464
	ds_read_b128 v[216:219], v162 offset:23072
	ds_read_b128 v[220:223], v161 offset:4640
	v_mfma_f32_32x32x16_bf16 v[18:33], v[176:179], v[168:171], v[18:33]
	v_mfma_f32_32x32x16_bf16 v[2:17], v[176:179], v[172:175], v[2:17]
	v_mfma_f32_32x32x16_bf16 v[50:65], v[180:183], v[184:187], v[50:65]
	v_mfma_f32_32x32x16_bf16 v[34:49], v[180:183], v[188:191], v[34:49]
	v_mfma_f32_32x32x16_bf16 v[18:33], v[224:227], v[184:187], v[18:33]
	v_mfma_f32_32x32x16_bf16 v[2:17], v[224:227], v[188:191], v[2:17]
	s_cbranch_vccz .LBB0_1682

.LBB0_1734:
	s_cmp_gt_u32 s37, 13
	s_cselect_b64 s[20:21], -1, 0
	s_and_b64 vcc, exec, s[20:21]
	s_waitcnt lgkmcnt(4)
	v_mfma_f32_32x32x16_bf16 v[50:65], v[192:195], v[196:199], v[50:65]
	v_mfma_f32_32x32x16_bf16 v[34:49], v[192:195], v[200:203], v[34:49]
	v_mfma_f32_32x32x16_bf16 v[18:33], v[204:207], v[196:199], v[18:33]
	v_mfma_f32_32x32x16_bf16 v[2:17], v[204:207], v[200:203], v[2:17]
	ds_read_b128 v[164:167], v161 offset:64
	ds_read_b128 v[168:171], v162 offset:18496
	ds_read_b128 v[172:175], v162 offset:23104
	ds_read_b128 v[176:179], v161 offset:4672
	s_waitcnt lgkmcnt(4)
	v_mfma_f32_32x32x16_bf16 v[50:65], v[208:211], v[212:215], v[50:65]
	v_mfma_f32_32x32x16_bf16 v[34:49], v[208:211], v[216:219], v[34:49]
	v_mfma_f32_32x32x16_bf16 v[18:33], v[220:223], v[212:215], v[18:33]
	v_mfma_f32_32x32x16_bf16 v[2:17], v[220:223], v[216:219], v[2:17]
	ds_read_b128 v[180:183], v161 offset:96
	ds_read_b128 v[184:187], v162 offset:18528
	ds_read_b128 v[188:191], v162 offset:23136
	ds_read_b128 v[224:227], v161 offset:4704
	s_waitcnt lgkmcnt(4)
	v_mfma_f32_32x32x16_bf16 v[50:65], v[164:167], v[168:171], v[50:65]
	v_mfma_f32_32x32x16_bf16 v[34:49], v[164:167], v[172:175], v[34:49]
	s_waitcnt lgkmcnt(0)
	s_barrier
	ds_read_b128 v[192:195], v161 offset:36864
	ds_read_b128 v[196:199], v162 offset:55296
	ds_read_b128 v[200:203], v162 offset:59904
	ds_read_b128 v[204:207], v161 offset:41472
	ds_read_b128 v[208:211], v161 offset:36896
	ds_read_b128 v[212:215], v162 offset:55328
	ds_read_b128 v[216:219], v162 offset:59936
	ds_read_b128 v[220:223], v161 offset:41504
	v_mfma_f32_32x32x16_bf16 v[18:33], v[176:179], v[168:171], v[18:33]
	v_mfma_f32_32x32x16_bf16 v[2:17], v[176:179], v[172:175], v[2:17]
	v_mfma_f32_32x32x16_bf16 v[50:65], v[180:183], v[184:187], v[50:65]
	v_mfma_f32_32x32x16_bf16 v[34:49], v[180:183], v[188:191], v[34:49]
	v_mfma_f32_32x32x16_bf16 v[18:33], v[224:227], v[184:187], v[18:33]
	v_mfma_f32_32x32x16_bf16 v[2:17], v[224:227], v[188:191], v[2:17]
	s_cbranch_vccnz .LBB0_1723
	s_cmp_gt_u32 s37, 11
	s_waitcnt vmcnt(3)
	ds_write_b128 v154, v[86:89]
	ds_write_b128 v154, v[94:97] offset:18432
	s_waitcnt vmcnt(2)
	ds_write_b128 v154, v[110:113] offset:4608
	ds_write_b128 v154, v[98:101] offset:23040
	s_waitcnt vmcnt(1)
	ds_write_b128 v154, v[114:117] offset:9216
	ds_write_b128 v154, v[118:121] offset:27648
	s_waitcnt vmcnt(0)
	ds_write_b128 v154, v[122:125] offset:13824
	ds_write_b128 v154, v[126:129] offset:32256
	s_cbranch_scc1 .LBB0_1723
	v_lshl_add_u64 v[86:87], v[152:153], 0, v[136:137]
	v_add_co_u32_e32 v86, vcc, 0xa380000, v86
	v_mov_b32_e32 v100, 0
	s_nop 0
	v_addc_co_u32_e32 v87, vcc, 0, v87, vcc
	global_load_dwordx4 v[86:89], v[86:87], off offset:512
	v_mov_b32_e32 v101, v130
	v_mov_b64_e32 v[96:97], v[100:101]
	v_mov_b64_e32 v[94:95], v[100:101]
	s_and_saveexec_b64 s[22:23], s[4:5]
	s_cbranch_execz .LBB0_1738
	v_lshl_add_u64 v[94:95], v[150:151], 0, v[136:137]
	v_add_co_u32_e32 v94, vcc, 0x89c0000, v94
	s_nop 1
	v_addc_co_u32_e32 v95, vcc, 0, v95, vcc
	global_load_dwordx4 v[94:97], v[94:95], off offset:512

.LBB0_2922:
	s_or_b64 exec, exec, s[20:21]
	v_add_u32_e32 v4, s35, v158
	v_ashrrev_i32_e32 v5, 31, v4
	v_lshlrev_b64 v[4:5], 12, v[4:5]
	v_lshl_add_u64 v[140:141], s[82:83], 0, v[4:5]
	v_add_u32_e32 v4, s35, v159
	v_ashrrev_i32_e32 v5, 31, v4
	v_lshlrev_b64 v[4:5], 12, v[4:5]
	v_lshl_add_u64 v[144:145], s[82:83], 0, v[4:5]
	v_add_u32_e32 v4, s35, v160
	v_ashrrev_i32_e32 v5, 31, v4
	v_lshlrev_b64 v[4:5], 12, v[4:5]
	v_lshl_add_u64 v[148:149], s[82:83], 0, v[4:5]
	v_add_u32_e32 v4, s35, v1
	v_ashrrev_i32_e32 v5, 31, v4
	v_lshlrev_b64 v[4:5], 12, v[4:5]
	v_lshl_add_u64 v[138:139], s[82:83], 0, v[48:49]
	v_lshl_add_u64 v[142:143], s[82:83], 0, v[42:43]
	v_lshl_add_u64 v[146:147], s[82:83], 0, v[36:37]
	v_lshl_add_u64 v[150:151], s[82:83], 0, v[34:35]
	v_lshl_add_u64 v[152:153], s[82:83], 0, v[4:5]
	s_mov_b32 s37, 0
	v_mov_b32_e32 v3, v2
	v_mov_b32_e32 v4, v2
	v_mov_b32_e32 v5, v2
	v_mov_b32_e32 v6, v2
	v_mov_b32_e32 v7, v2
	v_mov_b32_e32 v8, v2
	v_mov_b32_e32 v9, v2
	v_mov_b32_e32 v10, v2
	v_mov_b32_e32 v11, v2
	v_mov_b32_e32 v12, v2
	v_mov_b32_e32 v13, v2
	v_mov_b32_e32 v14, v2
	v_mov_b32_e32 v15, v2
	v_mov_b32_e32 v16, v2
	v_mov_b32_e32 v17, v2
	v_mov_b32_e32 v18, v2
	v_mov_b32_e32 v19, v2
	v_mov_b32_e32 v20, v2
	v_mov_b32_e32 v21, v2
	v_mov_b32_e32 v22, v2
	v_mov_b32_e32 v23, v2
	v_mov_b32_e32 v24, v2
	v_mov_b32_e32 v25, v2
	v_mov_b32_e32 v26, v2
	v_mov_b32_e32 v27, v2
	v_mov_b32_e32 v28, v2
	v_mov_b32_e32 v29, v2
	v_mov_b32_e32 v30, v2
	v_mov_b32_e32 v31, v2
	v_mov_b32_e32 v32, v2
	v_mov_b32_e32 v33, v2
	v_mov_b32_e32 v34, v2
	v_mov_b32_e32 v35, v2
	v_mov_b32_e32 v36, v2
	v_mov_b32_e32 v37, v2
	v_mov_b32_e32 v38, v2
	v_mov_b32_e32 v39, v2
	v_mov_b32_e32 v40, v2
	v_mov_b32_e32 v41, v2
	v_mov_b32_e32 v42, v2
	v_mov_b32_e32 v43, v2
	v_mov_b32_e32 v44, v2
	v_mov_b32_e32 v45, v2
	v_mov_b32_e32 v46, v2
	v_mov_b32_e32 v47, v2
	v_mov_b32_e32 v48, v2
	v_mov_b32_e32 v49, v2
	v_mov_b32_e32 v50, v2
	v_mov_b32_e32 v51, v2
	v_mov_b32_e32 v52, v2
	v_mov_b32_e32 v53, v2
	v_mov_b32_e32 v54, v2
	v_mov_b32_e32 v55, v2
	v_mov_b32_e32 v56, v2
	v_mov_b32_e32 v57, v2
	v_mov_b32_e32 v58, v2
	v_mov_b32_e32 v59, v2
	v_mov_b32_e32 v60, v2
	v_mov_b32_e32 v61, v2
	v_mov_b32_e32 v62, v2
	v_mov_b32_e32 v63, v2
	v_mov_b32_e32 v64, v2
	v_mov_b32_e32 v65, v2
	s_waitcnt lgkmcnt(0)
	s_barrier
	ds_read_b128 v[192:195], v161 offset:0
	ds_read_b128 v[196:199], v162 offset:18432
	ds_read_b128 v[200:203], v162 offset:23040
	ds_read_b128 v[204:207], v161 offset:4608
	ds_read_b128 v[208:211], v161 offset:32
	ds_read_b128 v[212:215], v162 offset:18464
	ds_read_b128 v[216:219], v162 offset:23072
	ds_read_b128 v[220:223], v161 offset:4640
	s_branch .LBB0_2925

.LBB0_2935:
	s_cmp_gt_u32 s37, 29
	s_cselect_b64 s[20:21], -1, 0
	s_and_b64 vcc, exec, s[20:21]
	s_waitcnt lgkmcnt(4)
	v_mfma_f32_32x32x16_bf16 v[50:65], v[192:195], v[196:199], v[50:65]
	v_mfma_f32_32x32x16_bf16 v[34:49], v[192:195], v[200:203], v[34:49]
	v_mfma_f32_32x32x16_bf16 v[18:33], v[204:207], v[196:199], v[18:33]
	v_mfma_f32_32x32x16_bf16 v[2:17], v[204:207], v[200:203], v[2:17]
	ds_read_b128 v[164:167], v161 offset:64
	ds_read_b128 v[168:171], v162 offset:18496
	ds_read_b128 v[172:175], v162 offset:23104
	ds_read_b128 v[176:179], v161 offset:4672
	s_waitcnt lgkmcnt(4)
	v_mfma_f32_32x32x16_bf16 v[50:65], v[208:211], v[212:215], v[50:65]
	v_mfma_f32_32x32x16_bf16 v[34:49], v[208:211], v[216:219], v[34:49]
	v_mfma_f32_32x32x16_bf16 v[18:33], v[220:223], v[212:215], v[18:33]
	v_mfma_f32_32x32x16_bf16 v[2:17], v[220:223], v[216:219], v[2:17]
	ds_read_b128 v[180:183], v161 offset:96
	ds_read_b128 v[184:187], v162 offset:18528
	ds_read_b128 v[188:191], v162 offset:23136
	ds_read_b128 v[224:227], v161 offset:4704
	s_waitcnt lgkmcnt(4)
	v_mfma_f32_32x32x16_bf16 v[50:65], v[164:167], v[168:171], v[50:65]
	v_mfma_f32_32x32x16_bf16 v[34:49], v[164:167], v[172:175], v[34:49]
	s_waitcnt lgkmcnt(0)
	s_barrier
	ds_read_b128 v[192:195], v161 offset:36864
	ds_read_b128 v[196:199], v162 offset:55296
	ds_read_b128 v[200:203], v162 offset:59904
	ds_read_b128 v[204:207], v161 offset:41472
	ds_read_b128 v[208:211], v161 offset:36896
	ds_read_b128 v[212:215], v162 offset:55328
	ds_read_b128 v[216:219], v162 offset:59936
	ds_read_b128 v[220:223], v161 offset:41504
	v_mfma_f32_32x32x16_bf16 v[18:33], v[176:179], v[168:171], v[18:33]
	v_mfma_f32_32x32x16_bf16 v[2:17], v[176:179], v[172:175], v[2:17]
	v_mfma_f32_32x32x16_bf16 v[50:65], v[180:183], v[184:187], v[50:65]
	v_mfma_f32_32x32x16_bf16 v[34:49], v[180:183], v[188:191], v[34:49]
	v_mfma_f32_32x32x16_bf16 v[18:33], v[224:227], v[184:187], v[18:33]
	v_mfma_f32_32x32x16_bf16 v[2:17], v[224:227], v[188:191], v[2:17]
	s_cbranch_vccnz .LBB0_2924
	s_cmp_gt_u32 s37, 27
	s_waitcnt vmcnt(3)
	ds_write_b128 v154, v[86:89]
	ds_write_b128 v154, v[94:97] offset:18432
	s_waitcnt vmcnt(2)
	ds_write_b128 v154, v[110:113] offset:4608
	ds_write_b128 v154, v[98:101] offset:23040
	s_waitcnt vmcnt(1)
	ds_write_b128 v154, v[114:117] offset:9216
	ds_write_b128 v154, v[118:121] offset:27648
	s_waitcnt vmcnt(0)
	ds_write_b128 v154, v[122:125] offset:13824
	ds_write_b128 v154, v[126:129] offset:32256
	s_cbranch_scc1 .LBB0_2924
	v_lshl_add_u64 v[86:87], v[152:153], 0, v[136:137]
	v_add_co_u32_e32 v86, vcc, 0x10740000, v86
	v_mov_b32_e32 v100, 0
	s_nop 0
	v_addc_co_u32_e32 v87, vcc, 0, v87, vcc
	global_load_dwordx4 v[86:89], v[86:87], off offset:512
	v_mov_b32_e32 v101, v130
	v_mov_b64_e32 v[96:97], v[100:101]
	v_mov_b64_e32 v[94:95], v[100:101]
	s_and_saveexec_b64 s[22:23], s[4:5]
	s_cbranch_execz .LBB0_2939
	v_lshl_add_u64 v[94:95], v[150:151], 0, v[136:137]
	v_add_co_u32_e32 v94, vcc, 0x95d0000, v94
	s_nop 1
	v_addc_co_u32_e32 v95, vcc, 0, v95, vcc
	global_load_dwordx4 v[94:97], v[94:95], off offset:512
